# f1 epilogue (bf16 residual path): residual rows of later quadrants loaded two quadrants ahead into epilogue-dead registers; quadrant 0's fourth load issued before its first wait
# baseline (speedup 1.0000x reference)
; template <int AI, int BJ>
; DI void f1_load(PREF p, int l, int mt, int dt, float4 (&xa)[4], float4 (&xb)[4]) {
;     ...
;   if (l == 0) {
; #pragma unroll
;     for (int q = 0; q < 4; ++q) {
;       const float4* xs = (const float4*)(p.x + (size_t)(row0 + (t >> 4) + 32 * q) * 1024 + col0 + c);
;       xa[q] = xs[0]; xb[q] = xs[1];
;     }
;   } else {
; #pragma unroll
;     for (int q = 0; q < 4; ++q) {
;       float f[8]; unpack8(*(const u32x4*)(p.X + (size_t)(row0 + (t >> 4) + 32 * q) * 1024 + col0 + c), f);
;       xa[q] = make_float4(f[0], f[1], f[2], f[3]); xb[q] = make_float4(f[4], f[5], f[6], f[7]);
;     }
;   }
.LBB0_69:
	s_or_b64 exec, exec, s[20:21]
	v_mov_b32_e32 v0, v168
	s_lshl_b32 s35, s35, 8
	v_lshlrev_b32_e32 v130, 3, v0
	v_ashrrev_i32_e32 v0, 4, v0
	s_lshl_b32 s20, s8, 8
	v_add_u32_e32 v164, s35, v0
	v_cndmask_b32_e64 v0, 0, 1, s[18:19]
	v_and_b32_e32 v162, 0x78, v130
	s_ashr_i32 s21, s20, 31
	v_cmp_ne_u32_e64 s[8:9], 1, v0
	s_andn2_b64 vcc, exec, s[18:19]
	v_ashrrev_i32_e32 v165, 31, v164
	s_cbranch_vccnz .LBB0_80
	s_lshl_b64 s[0:1], s[20:21], 1
	s_add_u32 s0, s12, s0
	s_addc_u32 s1, s13, s1
	v_lshlrev_b32_e32 v0, 1, v162
	v_lshl_add_u64 v[130:131], s[0:1], 0, v[0:1]
	v_lshlrev_b64 v[132:133], 11, v[164:165]
	v_lshl_add_u64 v[130:131], v[130:131], 0, v[132:133]
	v_add_co_u32_e32 v136, vcc, s88, v130
	s_mov_b32 s0, 0x20000
	s_nop 0
	v_addc_co_u32_e32 v137, vcc, 0, v131, vcc
	v_add_co_u32_e32 v140, vcc, s0, v130
	s_mov_b32 s0, 0x30000
	s_nop 0
	v_addc_co_u32_e32 v141, vcc, 0, v131, vcc
	v_mov_b32_e32 v252, v130
	v_mov_b32_e32 v253, v131
	global_load_dwordx4 v[132:135], v[130:131], off
	global_load_dwordx4 v[146:149], v[140:141], off
	s_nop 0
	global_load_dwordx4 v[136:139], v[136:137], off
	v_add_co_u32_e32 v130, vcc, s0, v130
	s_nop 1
	v_addc_co_u32_e32 v131, vcc, 0, v131, vcc
	global_load_dwordx4 v[182:185], v[130:131], off
	s_mov_b64 s[0:1], 0x10000
	global_load_dwordx4 v[186:189], v[252:253], off offset:256
	v_lshl_add_u64 v[252:253], v[252:253], 0, s[0:1]
	global_load_dwordx4 v[190:193], v[252:253], off offset:256
	v_lshl_add_u64 v[252:253], v[252:253], 0, s[0:1]
	global_load_dwordx4 v[194:197], v[252:253], off offset:256
	v_lshl_add_u64 v[252:253], v[252:253], 0, s[0:1]
	global_load_dwordx4 v[198:201], v[252:253], off offset:256
	v_lshl_add_u64 v[252:253], v[252:253], 0, s[0:1]
	v_mov_b32_e32 v214, v252
	v_mov_b32_e32 v215, v253
	global_load_dwordx4 v[202:205], v[252:253], off
	v_lshl_add_u64 v[252:253], v[252:253], 0, s[0:1]
	global_load_dwordx4 v[206:209], v[252:253], off
	v_lshl_add_u64 v[252:253], v[252:253], 0, s[0:1]
	global_load_dwordx4 v[210:213], v[252:253], off
	v_lshl_add_u64 v[252:253], v[252:253], 0, s[0:1]
	global_load_dwordx4 v[248:251], v[252:253], off
	s_waitcnt vmcnt(9)
	v_and_b32_e32 v151, 0xffff0000, v132
	v_lshlrev_b32_e32 v150, 16, v132
	v_and_b32_e32 v153, 0xffff0000, v133
	v_lshlrev_b32_e32 v152, 16, v133
	v_and_b32_e32 v131, 0xffff0000, v134
	v_lshlrev_b32_e32 v130, 16, v134
	v_and_b32_e32 v133, 0xffff0000, v135
	v_lshlrev_b32_e32 v132, 16, v135
	v_and_b32_e32 v143, 0xffff0000, v136
	v_lshlrev_b32_e32 v142, 16, v136
	v_and_b32_e32 v145, 0xffff0000, v137
	v_lshlrev_b32_e32 v144, 16, v137
	v_and_b32_e32 v135, 0xffff0000, v138
	v_lshlrev_b32_e32 v134, 16, v138
	v_and_b32_e32 v137, 0xffff0000, v139
	v_lshlrev_b32_e32 v136, 16, v139
	v_and_b32_e32 v155, 0xffff0000, v146
	v_lshlrev_b32_e32 v154, 16, v146
	v_and_b32_e32 v157, 0xffff0000, v147
	v_lshlrev_b32_e32 v156, 16, v147
	v_and_b32_e32 v139, 0xffff0000, v148
	v_lshlrev_b32_e32 v138, 16, v148
	v_and_b32_e32 v141, 0xffff0000, v149
	v_lshlrev_b32_e32 v140, 16, v149
	s_waitcnt vmcnt(8)
	v_and_b32_e32 v159, 0xffff0000, v182
	v_lshlrev_b32_e32 v158, 16, v182
	v_and_b32_e32 v161, 0xffff0000, v183
	v_lshlrev_b32_e32 v160, 16, v183
	v_and_b32_e32 v147, 0xffff0000, v184
	v_lshlrev_b32_e32 v146, 16, v184
	v_and_b32_e32 v149, 0xffff0000, v185
	v_lshlrev_b32_e32 v148, 16, v185
	s_cbranch_execnz .LBB0_72

; DI u32x4 pack8(const float* f) { u32x4 o; o.x = pack2(f[0], f[1]); o.y = pack2(f[2], f[3]); o.z = pack2(f[4], f[5]); o.w = pack2(f[6], f[7]); return o; }
; DI void lds_barrier() { asm volatile("s_waitcnt lgkmcnt(0)\n\ts_barrier" ::: "memory"); }
; DI int tid512() { int t = threadIdx.x; asm volatile("" : "+v"(t)); return t; }
; template <int AI, int BJ>
; DI void stage_q(const f32x4 (&acc)[2][2][4][2], float* Cs) {
;   const int t = tid512(), wid = t >> 6, lane = t & 63, wr = wid >> 2, wc = wid & 3, fr = lane & 15, fq = lane >> 4;
;   lds_barrier();
; #pragma unroll
;   for (int m = 0; m < 4; ++m)
; #pragma unroll
;     for (int n = 0; n < 2; ++n)
; #pragma unroll
;       for (int j = 0; j < 4; ++j) Cs[(wr * 64 + m * 16 + fq * 4 + j) * CST + wc * 32 + n * 16 + fr] = acc[AI][BJ][m][n][j];
;   lds_barrier();
; }
; template <int AI, int BJ>
; DI void f1_proc(PREF p, const f32x4 (&acc)[2][2][4][2], int mt, int dt, float* Cs, const float4 (&xa)[4], const float4 (&xb)[4]) {
;   const int t = tid512();
;   const int row0 = mt * 256 + AI * 128, col0 = dt * 256 + BJ * 128, c = (t & 15) * 8;
;   const float alpha = 1.681792830507429f;
;   stage_q<AI, BJ>(acc, Cs);
; #pragma unroll
;   for (int q = 0; q < 4; ++q) {
;     int r = (t >> 4) + 32 * q;
;     float v[8]; ld8(Cs + r * CST + c, v);
;     float4 a = xa[q], b = xb[q];
;     float y[8] = {alpha * a.x + v[0], alpha * a.y + v[1], alpha * a.z + v[2], alpha * a.w + v[3],
;                   alpha * b.x + v[4], alpha * b.y + v[5], alpha * b.z + v[6], alpha * b.w + v[7]};
;     *(u32x4*)((u16*)p.fbuf + (size_t)(row0 + r) * 1024 + col0 + c) = pack8(y);
;   }
.LBB0_72:
	v_mov_b32_e32 v162, v168
	s_lshl_b64 s[24:25], s[20:21], 1
	v_lshlrev_b32_e32 v0, 3, v162
	v_and_b32_e32 v166, 0x78, v0
	v_mov_b32_e32 v0, v168
	s_waitcnt lgkmcnt(0)
	s_barrier
	s_add_u32 s22, s16, s24
	v_and_b32_e32 v164, 15, v0
	v_lshrrev_b32_e32 v165, 2, v0
	v_lshlrev_b32_e32 v0, 1, v0
	v_lshlrev_b32_e32 v164, 2, v164
	v_and_b32_e32 v165, 0xfffffcc, v165
	v_and_or_b32 v0, v0, s89, v164
	v_mad_u64_u32 v[164:165], s[0:1], v165, s92, v[0:1]
	v_add_u32_e32 v0, 0x400, v164
	ds_write2_b32 v164, v118, v126 offset1:16
	ds_write2_b32 v164, v119, v127 offset0:132 offset1:148
	ds_write2_b32 v0, v120, v128 offset0:8 offset1:24
	ds_write2_b32 v0, v121, v129 offset0:140 offset1:156
	v_add_u32_e32 v0, 0x2000, v164
	ds_write2_b32 v0, v114, v122 offset0:64 offset1:80
	ds_write2_b32 v0, v115, v123 offset0:196 offset1:212
	v_add_u32_e32 v0, 0x2400, v164
	ds_write2_b32 v0, v116, v124 offset0:72 offset1:88
	ds_write2_b32 v0, v117, v125 offset0:204 offset1:220
	v_add_u32_e32 v0, 0x4000, v164
	ds_write2_b32 v0, v106, v110 offset0:128 offset1:144
	v_add_u32_e32 v0, 0x4400, v164
	ds_write2_b32 v0, v107, v111 offset0:4 offset1:20
	ds_write2_b32 v0, v108, v112 offset0:136 offset1:152
	v_add_u32_e32 v0, 0x4800, v164
	ds_write2_b32 v0, v109, v113 offset0:12 offset1:28
	v_add_u32_e32 v0, 0x6000, v164
	ds_write2_b32 v0, v98, v102 offset0:192 offset1:208
	v_add_u32_e32 v0, 0x6400, v164
	ds_write2_b32 v0, v99, v103 offset0:68 offset1:84
	ds_write2_b32 v0, v100, v104 offset0:200 offset1:216
	v_add_u32_e32 v0, 0x6800, v164
	v_ashrrev_i32_e32 v108, 4, v162
	ds_write2_b32 v0, v101, v105 offset0:76 offset1:92
	v_mul_lo_u32 v0, v108, s92
	s_waitcnt lgkmcnt(0)
	s_barrier
	v_lshl_add_u32 v112, v166, 2, v0
	s_waitcnt vmcnt(0)
	ds_read_b128 v[98:101], v112
	ds_read_b128 v[102:105], v112 offset:16
	v_add_u32_e32 v108, s35, v108
	s_addc_u32 s23, s17, s25
	v_lshlrev_b32_e32 v0, 1, v166
	v_ashrrev_i32_e32 v109, 31, v108
	v_lshl_add_u64 v[106:107], s[22:23], 0, v[0:1]
	s_waitcnt lgkmcnt(1)
	v_fmamk_f32 v0, v150, 0x3fd744fd, v98
	v_fmamk_f32 v98, v151, 0x3fd744fd, v99
	v_fmamk_f32 v99, v152, 0x3fd744fd, v100
	v_fmac_f32_e32 v101, 0x3fd744fd, v153
	s_waitcnt lgkmcnt(0)
	v_fmamk_f32 v100, v130, 0x3fd744fd, v102
	v_lshlrev_b64 v[110:111], 11, v[108:109]
	v_fmamk_f32 v102, v131, 0x3fd744fd, v103
	v_fmamk_f32 v103, v132, 0x3fd744fd, v104
	v_fmac_f32_e32 v105, 0x3fd744fd, v133
	v_cvt_pk_bf16_f32 v98, v0, v98
	v_cvt_pk_bf16_f32 v99, v99, v101
	v_cvt_pk_bf16_f32 v100, v100, v102
	v_cvt_pk_bf16_f32 v101, v103, v105
	v_lshl_add_u64 v[110:111], v[106:107], 0, v[110:111]
	ds_read_b128 v[102:105], v112 offset:16896
	global_store_dwordx4 v[110:111], v[98:101], off
	ds_read_b128 v[98:101], v112 offset:16912
	s_and_b64 vcc, exec, s[8:9]
	s_waitcnt lgkmcnt(1)
	v_fmamk_f32 v0, v142, 0x3fd744fd, v102
	v_fmamk_f32 v102, v143, 0x3fd744fd, v103
	s_waitcnt lgkmcnt(0)
	v_fmamk_f32 v110, v136, 0x3fd744fd, v100
	v_fmac_f32_e32 v101, 0x3fd744fd, v137
	v_cvt_pk_bf16_f32 v101, v110, v101
	v_add_u32_e32 v110, 32, v108
	v_ashrrev_i32_e32 v111, 31, v110
	v_lshlrev_b64 v[110:111], 11, v[110:111]
	v_fmamk_f32 v103, v144, 0x3fd744fd, v104
	v_fmac_f32_e32 v105, 0x3fd744fd, v145
	v_fmamk_f32 v104, v134, 0x3fd744fd, v98
	v_fmamk_f32 v109, v135, 0x3fd744fd, v99
	v_cvt_pk_bf16_f32 v98, v0, v102
	v_cvt_pk_bf16_f32 v99, v103, v105
	v_cvt_pk_bf16_f32 v100, v104, v109
	v_lshl_add_u64 v[110:111], v[106:107], 0, v[110:111]
	ds_read_b128 v[102:105], v112 offset:33792
	global_store_dwordx4 v[110:111], v[98:101], off
	ds_read_b128 v[98:101], v112 offset:33808
	s_waitcnt lgkmcnt(1)
	v_fmamk_f32 v0, v154, 0x3fd744fd, v102
	v_fmamk_f32 v102, v155, 0x3fd744fd, v103
	s_waitcnt lgkmcnt(0)
	v_fmamk_f32 v110, v140, 0x3fd744fd, v100
	v_fmac_f32_e32 v101, 0x3fd744fd, v141
	v_cvt_pk_bf16_f32 v101, v110, v101
	v_add_u32_e32 v110, 64, v108
	v_ashrrev_i32_e32 v111, 31, v110
	v_fmamk_f32 v103, v156, 0x3fd744fd, v104
	v_fmac_f32_e32 v105, 0x3fd744fd, v157
	v_fmamk_f32 v104, v138, 0x3fd744fd, v98
	v_lshlrev_b64 v[110:111], 11, v[110:111]
	v_fmamk_f32 v109, v139, 0x3fd744fd, v99
	v_cvt_pk_bf16_f32 v98, v0, v102
	v_cvt_pk_bf16_f32 v99, v103, v105
	v_cvt_pk_bf16_f32 v100, v104, v109
	ds_read_b128 v[102:105], v112 offset:50688
	v_lshl_add_u64 v[110:111], v[106:107], 0, v[110:111]
	global_store_dwordx4 v[110:111], v[98:101], off
	ds_read_b128 v[98:101], v112 offset:50704
	s_waitcnt lgkmcnt(1)
	v_fmamk_f32 v0, v158, 0x3fd744fd, v102
	v_fmamk_f32 v102, v159, 0x3fd744fd, v103
	v_fmamk_f32 v103, v160, 0x3fd744fd, v104
	s_waitcnt lgkmcnt(0)
	v_fmamk_f32 v104, v146, 0x3fd744fd, v98
	v_cvt_pk_bf16_f32 v98, v0, v102
	v_add_u32_e32 v102, 0x60, v108
	v_fmac_f32_e32 v105, 0x3fd744fd, v161
	v_fmamk_f32 v109, v147, 0x3fd744fd, v99
	v_cvt_pk_bf16_f32 v99, v103, v105
	v_ashrrev_i32_e32 v103, 31, v102
	v_lshlrev_b64 v[102:103], 11, v[102:103]
	v_fmac_f32_e32 v101, 0x3fd744fd, v149
	v_lshl_add_u64 v[102:103], v[106:107], 0, v[102:103]
	v_mov_b32_e32 v0, v168
	v_fmamk_f32 v110, v148, 0x3fd744fd, v100
	v_cvt_pk_bf16_f32 v100, v104, v109
	v_cvt_pk_bf16_f32 v101, v110, v101
	global_store_dwordx4 v[102:103], v[98:101], off
	s_nop 1
	v_lshlrev_b32_e32 v98, 3, v0
	v_ashrrev_i32_e32 v0, 4, v0
	v_add_u32_e32 v130, s35, v0
	v_and_b32_e32 v132, 0x78, v98
	v_ashrrev_i32_e32 v131, 31, v130
	s_cbranch_vccnz .LBB0_81
; template <int AI, int BJ>
; DI void f1_load(PREF p, int l, int mt, int dt, float4 (&xa)[4], float4 (&xb)[4]) {
;     ...
;   } else {
; #pragma unroll
;     for (int q = 0; q < 4; ++q) {
;       float f[8]; unpack8(*(const u32x4*)(p.X + (size_t)(row0 + (t >> 4) + 32 * q) * 1024 + col0 + c), f);
;       xa[q] = make_float4(f[0], f[1], f[2], f[3]); xb[q] = make_float4(f[4], f[5], f[6], f[7]);
;     }
;   }
	s_add_u32 s0, s12, s24
	s_addc_u32 s1, s13, s25
	v_lshlrev_b32_e32 v0, 1, v132
	v_lshl_add_u64 v[98:99], s[0:1], 0, v[0:1]
	v_lshlrev_b64 v[100:101], 11, v[130:131]
	v_lshl_add_u64 v[102:103], v[98:99], 0, v[100:101]
	v_add_co_u32_e32 v104, vcc, s88, v102
	s_mov_b32 s0, 0x20000
	s_nop 0
	v_addc_co_u32_e32 v105, vcc, 0, v103, vcc
	v_add_co_u32_e32 v104, vcc, s0, v102
	s_mov_b32 s0, 0x30000
	s_nop 0
	v_addc_co_u32_e32 v105, vcc, 0, v103, vcc
	v_add_co_u32_e32 v102, vcc, s0, v102
	s_nop 0
	s_nop 0
	v_addc_co_u32_e32 v103, vcc, 0, v103, vcc
	s_waitcnt vmcnt(4)
	v_and_b32_e32 v127, 0xffff0000, v186
	v_lshlrev_b32_e32 v126, 16, v186
	v_and_b32_e32 v129, 0xffff0000, v187
	v_lshlrev_b32_e32 v128, 16, v187
	v_and_b32_e32 v103, 0xffff0000, v188
	v_lshlrev_b32_e32 v102, 16, v188
	v_and_b32_e32 v105, 0xffff0000, v189
	v_lshlrev_b32_e32 v104, 16, v189
	s_waitcnt vmcnt(4)
	v_and_b32_e32 v115, 0xffff0000, v190
	v_lshlrev_b32_e32 v114, 16, v190
	v_and_b32_e32 v117, 0xffff0000, v191
	v_lshlrev_b32_e32 v116, 16, v191
	v_and_b32_e32 v99, 0xffff0000, v192
	v_lshlrev_b32_e32 v98, 16, v192
	v_and_b32_e32 v101, 0xffff0000, v193
	v_lshlrev_b32_e32 v100, 16, v193
	s_waitcnt vmcnt(4)
	v_and_b32_e32 v119, 0xffff0000, v194
	v_lshlrev_b32_e32 v118, 16, v194
	v_and_b32_e32 v121, 0xffff0000, v195
	v_lshlrev_b32_e32 v120, 16, v195
	v_and_b32_e32 v107, 0xffff0000, v196
	v_lshlrev_b32_e32 v106, 16, v196
	v_and_b32_e32 v109, 0xffff0000, v197
	v_lshlrev_b32_e32 v108, 16, v197
	s_waitcnt vmcnt(4)
	v_and_b32_e32 v123, 0xffff0000, v198
	v_lshlrev_b32_e32 v122, 16, v198
	v_and_b32_e32 v125, 0xffff0000, v199
	v_lshlrev_b32_e32 v124, 16, v199
	v_and_b32_e32 v111, 0xffff0000, v200
	v_lshlrev_b32_e32 v110, 16, v200
	v_and_b32_e32 v113, 0xffff0000, v201
	v_lshlrev_b32_e32 v112, 16, v201
	s_mov_b64 s[0:1], 0x10000
	global_load_dwordx4 v[186:189], v[214:215], off offset:256
	v_lshl_add_u64 v[214:215], v[214:215], 0, s[0:1]
	global_load_dwordx4 v[190:193], v[214:215], off offset:256
	v_lshl_add_u64 v[214:215], v[214:215], 0, s[0:1]
	global_load_dwordx4 v[194:197], v[214:215], off offset:256
	v_lshl_add_u64 v[214:215], v[214:215], 0, s[0:1]
	global_load_dwordx4 v[198:201], v[214:215], off offset:256
	s_cbranch_execnz .LBB0_75

; DI u32x4 pack8(const float* f) { u32x4 o; o.x = pack2(f[0], f[1]); o.y = pack2(f[2], f[3]); o.z = pack2(f[4], f[5]); o.w = pack2(f[6], f[7]); return o; }
; DI int tid512() { int t = threadIdx.x; asm volatile("" : "+v"(t)); return t; }
; template <int AI, int BJ>
; DI void f1_load(PREF p, int l, int mt, int dt, float4 (&xa)[4], float4 (&xb)[4]) {
;     ...
;   } else {
; #pragma unroll
;     for (int q = 0; q < 4; ++q) {
;       float f[8]; unpack8(*(const u32x4*)(p.X + (size_t)(row0 + (t >> 4) + 32 * q) * 1024 + col0 + c), f);
;       xa[q] = make_float4(f[0], f[1], f[2], f[3]); xb[q] = make_float4(f[4], f[5], f[6], f[7]);
;     }
;   }
; template <int AI, int BJ>
; DI void f1_proc(PREF p, const f32x4 (&acc)[2][2][4][2], int mt, int dt, float* Cs, const float4 (&xa)[4], const float4 (&xb)[4]) {
;   const int t = tid512();
;   const int row0 = mt * 256 + AI * 128, col0 = dt * 256 + BJ * 128, c = (t & 15) * 8;
;   const float alpha = 1.681792830507429f;
;   stage_q<AI, BJ>(acc, Cs);
; #pragma unroll
;   for (int q = 0; q < 4; ++q) {
;     int r = (t >> 4) + 32 * q;
;     float v[8]; ld8(Cs + r * CST + c, v);
;     float4 a = xa[q], b = xb[q];
;     float y[8] = {alpha * a.x + v[0], alpha * a.y + v[1], alpha * a.z + v[2], alpha * a.w + v[3],
;                   alpha * b.x + v[4], alpha * b.y + v[5], alpha * b.z + v[6], alpha * b.w + v[7]};
;     *(u32x4*)((u16*)p.fbuf + (size_t)(row0 + r) * 1024 + col0 + c) = pack8(y);
;   }
.LBB0_75:
	v_mov_b32_e32 v132, v168
	s_and_b64 vcc, exec, s[8:9]
	v_lshlrev_b32_e32 v0, 3, v132
	v_and_b32_e32 v133, 0x78, v0
	v_mov_b32_e32 v0, v168
	s_waitcnt lgkmcnt(0)
	s_barrier
	s_nop 0
	v_and_b32_e32 v130, 15, v0
	v_lshrrev_b32_e32 v131, 2, v0
	v_lshlrev_b32_e32 v0, 1, v0
	v_lshlrev_b32_e32 v130, 2, v130
	v_and_b32_e32 v131, 0xfffffcc, v131
	v_and_or_b32 v0, v0, s89, v130
	v_mad_u64_u32 v[130:131], s[0:1], v131, s92, v[0:1]
	v_add_u32_e32 v0, 0x400, v130
	ds_write2_b32 v130, v86, v94 offset1:16
	ds_write2_b32 v130, v87, v95 offset0:132 offset1:148
	ds_write2_b32 v0, v88, v96 offset0:8 offset1:24
	ds_write2_b32 v0, v89, v97 offset0:140 offset1:156
	v_add_u32_e32 v0, 0x2000, v130
	ds_write2_b32 v0, v82, v90 offset0:64 offset1:80
	ds_write2_b32 v0, v83, v91 offset0:196 offset1:212
	v_add_u32_e32 v0, 0x2400, v130
	ds_write2_b32 v0, v84, v92 offset0:72 offset1:88
	ds_write2_b32 v0, v85, v93 offset0:204 offset1:220
	v_add_u32_e32 v0, 0x4000, v130
	ds_write2_b32 v0, v74, v78 offset0:128 offset1:144
	v_add_u32_e32 v0, 0x4400, v130
	ds_write2_b32 v0, v75, v79 offset0:4 offset1:20
	ds_write2_b32 v0, v76, v80 offset0:136 offset1:152
	v_add_u32_e32 v0, 0x4800, v130
	ds_write2_b32 v0, v77, v81 offset0:12 offset1:28
	v_add_u32_e32 v0, 0x6000, v130
	ds_write2_b32 v0, v66, v70 offset0:192 offset1:208
	v_add_u32_e32 v0, 0x6400, v130
	ds_write2_b32 v0, v67, v71 offset0:68 offset1:84
	ds_write2_b32 v0, v68, v72 offset0:200 offset1:216
	v_add_u32_e32 v0, 0x6800, v130
	ds_write2_b32 v0, v69, v73 offset0:76 offset1:92
	v_ashrrev_i32_e32 v0, 4, v132
	v_mul_lo_u32 v66, v0, s92
	s_waitcnt lgkmcnt(0)
	s_barrier
	v_lshl_add_u32 v78, v133, 2, v66
	ds_read_b128 v[66:69], v78
	ds_read_b128 v[70:73], v78 offset:16
	v_add_u32_e32 v74, s35, v0
	v_ashrrev_i32_e32 v75, 31, v74
	v_lshlrev_b32_e32 v0, 1, v133
	s_waitcnt vmcnt(6) lgkmcnt(1)
	v_fmamk_f32 v66, v126, 0x3fd744fd, v66
	v_fmamk_f32 v67, v127, 0x3fd744fd, v67
	v_fmamk_f32 v68, v128, 0x3fd744fd, v68
	s_waitcnt lgkmcnt(0)
	v_fmamk_f32 v70, v102, 0x3fd744fd, v70
	v_fmamk_f32 v71, v103, 0x3fd744fd, v71
	v_fmac_f32_e32 v69, 0x3fd744fd, v129
	v_cvt_pk_bf16_f32 v66, v66, v67
	v_cvt_pk_bf16_f32 v67, v68, v69
	v_cvt_pk_bf16_f32 v68, v70, v71
	v_lshlrev_b64 v[70:71], 11, v[74:75]
	v_fmamk_f32 v72, v104, 0x3fd744fd, v72
	v_fmac_f32_e32 v73, 0x3fd744fd, v105
	v_lshl_add_u64 v[76:77], s[22:23], 0, v[70:71]
	v_cvt_pk_bf16_f32 v69, v72, v73
	ds_read_b128 v[70:73], v78 offset:16896
	v_lshl_add_u64 v[76:77], v[76:77], 0, v[0:1]
	global_store_dwordx4 v[76:77], v[66:69], off offset:256
	ds_read_b128 v[66:69], v78 offset:16912
	s_bitset1_b32 s35, 7
	s_waitcnt vmcnt(6) lgkmcnt(1)
	v_fmamk_f32 v70, v114, 0x3fd744fd, v70
	v_fmamk_f32 v71, v115, 0x3fd744fd, v71
	v_fmamk_f32 v72, v116, 0x3fd744fd, v72
	s_waitcnt vmcnt(5) lgkmcnt(0)
	v_fmamk_f32 v75, v98, 0x3fd744fd, v66
	v_cvt_pk_bf16_f32 v66, v70, v71
	v_add_u32_e32 v70, 32, v74
	v_fmamk_f32 v76, v99, 0x3fd744fd, v67
	v_fmamk_f32 v77, v100, 0x3fd744fd, v68
	v_fmac_f32_e32 v69, 0x3fd744fd, v101
	v_ashrrev_i32_e32 v71, 31, v70
	v_cvt_pk_bf16_f32 v68, v75, v76
	v_cvt_pk_bf16_f32 v69, v77, v69
	v_lshlrev_b64 v[76:77], 11, v[70:71]
	v_fmac_f32_e32 v73, 0x3fd744fd, v117
	v_lshl_add_u64 v[76:77], s[22:23], 0, v[76:77]
	v_cvt_pk_bf16_f32 v67, v72, v73
	ds_read_b128 v[70:73], v78 offset:33792
	v_lshl_add_u64 v[76:77], v[76:77], 0, v[0:1]
	global_store_dwordx4 v[76:77], v[66:69], off offset:256
	ds_read_b128 v[66:69], v78 offset:33808
	s_waitcnt vmcnt(5) lgkmcnt(1)
	v_fmamk_f32 v70, v118, 0x3fd744fd, v70
	v_fmamk_f32 v71, v119, 0x3fd744fd, v71
	v_fmamk_f32 v72, v120, 0x3fd744fd, v72
	s_waitcnt vmcnt(4) lgkmcnt(0)
	v_fmamk_f32 v75, v106, 0x3fd744fd, v66
	v_cvt_pk_bf16_f32 v66, v70, v71
	v_add_u32_e32 v70, 64, v74
	v_fmamk_f32 v76, v107, 0x3fd744fd, v67
	v_fmamk_f32 v77, v108, 0x3fd744fd, v68
	v_fmac_f32_e32 v69, 0x3fd744fd, v109
	v_ashrrev_i32_e32 v71, 31, v70
	v_cvt_pk_bf16_f32 v68, v75, v76
	v_cvt_pk_bf16_f32 v69, v77, v69
	v_lshlrev_b64 v[76:77], 11, v[70:71]
	v_fmac_f32_e32 v73, 0x3fd744fd, v121
	v_lshl_add_u64 v[76:77], s[22:23], 0, v[76:77]
	v_cvt_pk_bf16_f32 v67, v72, v73
	ds_read_b128 v[70:73], v78 offset:50688
	v_lshl_add_u64 v[76:77], v[76:77], 0, v[0:1]
	global_store_dwordx4 v[76:77], v[66:69], off offset:256
	ds_read_b128 v[66:69], v78 offset:50704
	s_waitcnt vmcnt(4) lgkmcnt(1)
	v_fmamk_f32 v70, v122, 0x3fd744fd, v70
	v_fmamk_f32 v71, v123, 0x3fd744fd, v71
	v_fmamk_f32 v72, v124, 0x3fd744fd, v72
	s_waitcnt vmcnt(3) lgkmcnt(0)
	v_fmamk_f32 v75, v110, 0x3fd744fd, v66
	v_cvt_pk_bf16_f32 v66, v70, v71
	v_add_u32_e32 v70, 0x60, v74
	v_ashrrev_i32_e32 v71, 31, v70
	v_lshlrev_b64 v[70:71], 11, v[70:71]
	v_lshl_add_u64 v[70:71], s[22:23], 0, v[70:71]
	v_fmac_f32_e32 v69, 0x3fd744fd, v113
	v_lshl_add_u64 v[70:71], v[70:71], 0, v[0:1]
	v_mov_b32_e32 v0, v168
	v_fmac_f32_e32 v73, 0x3fd744fd, v125
	v_fmamk_f32 v76, v111, 0x3fd744fd, v67
	v_fmamk_f32 v77, v112, 0x3fd744fd, v68
	v_cvt_pk_bf16_f32 v67, v72, v73
	v_cvt_pk_bf16_f32 v68, v75, v76
	v_cvt_pk_bf16_f32 v69, v77, v69
	global_store_dwordx4 v[70:71], v[66:69], off offset:256
	s_nop 1
	v_lshlrev_b32_e32 v66, 3, v0
	v_ashrrev_i32_e32 v0, 4, v0
	v_add_u32_e32 v98, s35, v0
	v_and_b32_e32 v100, 0x78, v66
	v_ashrrev_i32_e32 v99, 31, v98
	s_cbranch_vccnz .LBB0_82
	s_add_u32 s0, s12, s24
	s_addc_u32 s1, s13, s25
	v_lshlrev_b32_e32 v0, 1, v100
	v_lshl_add_u64 v[66:67], s[0:1], 0, v[0:1]
	v_lshlrev_b64 v[68:69], 11, v[98:99]
	v_lshl_add_u64 v[66:67], v[66:67], 0, v[68:69]
	v_add_co_u32_e32 v72, vcc, s88, v66
	s_mov_b32 s0, 0x20000
	s_nop 0
	v_addc_co_u32_e32 v73, vcc, 0, v67, vcc
	v_add_co_u32_e32 v76, vcc, s0, v66
	s_mov_b32 s0, 0x30000
	s_nop 0
	v_addc_co_u32_e32 v77, vcc, 0, v67, vcc
	s_nop 0
	v_add_co_u32_e32 v66, vcc, s0, v66
	s_waitcnt vmcnt(4)
	v_and_b32_e32 v87, 0xffff0000, v202
	v_addc_co_u32_e32 v67, vcc, 0, v67, vcc
	v_lshlrev_b32_e32 v86, 16, v202
	v_and_b32_e32 v89, 0xffff0000, v203
	v_lshlrev_b32_e32 v88, 16, v203
	v_and_b32_e32 v67, 0xffff0000, v204
	v_lshlrev_b32_e32 v66, 16, v204
	v_and_b32_e32 v69, 0xffff0000, v205
	v_lshlrev_b32_e32 v68, 16, v205
	s_waitcnt vmcnt(4)
	v_and_b32_e32 v79, 0xffff0000, v206
	v_lshlrev_b32_e32 v78, 16, v206
	v_and_b32_e32 v81, 0xffff0000, v207
	v_lshlrev_b32_e32 v80, 16, v207
	v_and_b32_e32 v71, 0xffff0000, v208
	v_lshlrev_b32_e32 v70, 16, v208
	v_and_b32_e32 v73, 0xffff0000, v209
	v_lshlrev_b32_e32 v72, 16, v209
	v_and_b32_e32 v91, 0xffff0000, v210
	v_lshlrev_b32_e32 v90, 16, v210
	v_and_b32_e32 v93, 0xffff0000, v211
	v_lshlrev_b32_e32 v92, 16, v211
	v_and_b32_e32 v75, 0xffff0000, v212
	v_lshlrev_b32_e32 v74, 16, v212
	v_and_b32_e32 v77, 0xffff0000, v213
	v_lshlrev_b32_e32 v76, 16, v213
	s_waitcnt vmcnt(4)
	v_and_b32_e32 v95, 0xffff0000, v248
	v_lshlrev_b32_e32 v94, 16, v248
	v_and_b32_e32 v97, 0xffff0000, v249
	v_lshlrev_b32_e32 v96, 16, v249
	v_and_b32_e32 v83, 0xffff0000, v250
	v_lshlrev_b32_e32 v82, 16, v250
	v_and_b32_e32 v85, 0xffff0000, v251
	v_lshlrev_b32_e32 v84, 16, v251
	s_cbranch_execnz .LBB0_78

; DI u32x4 pack8(const float* f) { u32x4 o; o.x = pack2(f[0], f[1]); o.y = pack2(f[2], f[3]); o.z = pack2(f[4], f[5]); o.w = pack2(f[6], f[7]); return o; }
; DI int tid512() { int t = threadIdx.x; asm volatile("" : "+v"(t)); return t; }
; template <int AI, int BJ>
; DI void f1_load(PREF p, int l, int mt, int dt, float4 (&xa)[4], float4 (&xb)[4]) {
;     ...
;   } else {
; #pragma unroll
;     for (int q = 0; q < 4; ++q) {
;       float f[8]; unpack8(*(const u32x4*)(p.X + (size_t)(row0 + (t >> 4) + 32 * q) * 1024 + col0 + c), f);
;       xa[q] = make_float4(f[0], f[1], f[2], f[3]); xb[q] = make_float4(f[4], f[5], f[6], f[7]);
;     }
;   }
; template <int AI, int BJ>
; DI void f1_proc(PREF p, const f32x4 (&acc)[2][2][4][2], int mt, int dt, float* Cs, const float4 (&xa)[4], const float4 (&xb)[4]) {
;   const int t = tid512();
;   const int row0 = mt * 256 + AI * 128, col0 = dt * 256 + BJ * 128, c = (t & 15) * 8;
;   const float alpha = 1.681792830507429f;
;   stage_q<AI, BJ>(acc, Cs);
; #pragma unroll
;   for (int q = 0; q < 4; ++q) {
;     int r = (t >> 4) + 32 * q;
;     float v[8]; ld8(Cs + r * CST + c, v);
;     float4 a = xa[q], b = xb[q];
;     float y[8] = {alpha * a.x + v[0], alpha * a.y + v[1], alpha * a.z + v[2], alpha * a.w + v[3],
;                   alpha * b.x + v[4], alpha * b.y + v[5], alpha * b.z + v[6], alpha * b.w + v[7]};
;     *(u32x4*)((u16*)p.fbuf + (size_t)(row0 + r) * 1024 + col0 + c) = pack8(y);
;   }
.LBB0_78:
	v_mov_b32_e32 v100, v168
	s_and_b64 vcc, exec, s[8:9]
	v_lshlrev_b32_e32 v0, 3, v100
	v_and_b32_e32 v101, 0x78, v0
	v_mov_b32_e32 v0, v168
	s_waitcnt lgkmcnt(0)
	s_barrier
	s_nop 0
	v_and_b32_e32 v98, 15, v0
	v_lshrrev_b32_e32 v99, 2, v0
	v_lshlrev_b32_e32 v0, 1, v0
	v_lshlrev_b32_e32 v98, 2, v98
	v_and_b32_e32 v99, 0xfffffcc, v99
	v_and_or_b32 v0, v0, s89, v98
	v_mad_u64_u32 v[98:99], s[0:1], v99, s92, v[0:1]
	v_add_u32_e32 v0, 0x400, v98
	ds_write2_b32 v98, v54, v62 offset1:16
	ds_write2_b32 v98, v55, v63 offset0:132 offset1:148
	ds_write2_b32 v0, v56, v64 offset0:8 offset1:24
	ds_write2_b32 v0, v57, v65 offset0:140 offset1:156
	v_add_u32_e32 v0, 0x2000, v98
	ds_write2_b32 v0, v50, v58 offset0:64 offset1:80
	ds_write2_b32 v0, v51, v59 offset0:196 offset1:212
	v_add_u32_e32 v0, 0x2400, v98
	ds_write2_b32 v0, v52, v60 offset0:72 offset1:88
	ds_write2_b32 v0, v53, v61 offset0:204 offset1:220
	v_add_u32_e32 v0, 0x4000, v98
	ds_write2_b32 v0, v42, v46 offset0:128 offset1:144
	v_add_u32_e32 v0, 0x4400, v98
	ds_write2_b32 v0, v43, v47 offset0:4 offset1:20
	ds_write2_b32 v0, v44, v48 offset0:136 offset1:152
	v_add_u32_e32 v0, 0x4800, v98
	ds_write2_b32 v0, v45, v49 offset0:12 offset1:28
	v_add_u32_e32 v0, 0x6000, v98
	ds_write2_b32 v0, v34, v38 offset0:192 offset1:208
	v_add_u32_e32 v0, 0x6400, v98
	ds_write2_b32 v0, v35, v39 offset0:68 offset1:84
	ds_write2_b32 v0, v36, v40 offset0:200 offset1:216
	v_add_u32_e32 v0, 0x6800, v98
	v_ashrrev_i32_e32 v44, 4, v100
	ds_write2_b32 v0, v37, v41 offset0:76 offset1:92
	v_mul_lo_u32 v0, v44, s92
	s_waitcnt lgkmcnt(0)
	s_barrier
	v_lshl_add_u32 v48, v101, 2, v0
	ds_read_b128 v[34:37], v48
	ds_read_b128 v[38:41], v48 offset:16
	v_add_u32_e32 v44, s35, v44
	v_lshlrev_b32_e32 v0, 1, v101
	v_ashrrev_i32_e32 v45, 31, v44
	v_lshl_add_u64 v[42:43], s[22:23], 0, v[0:1]
	s_waitcnt vmcnt(6) lgkmcnt(1)
	v_fmamk_f32 v0, v86, 0x3fd744fd, v34
	v_fmamk_f32 v34, v87, 0x3fd744fd, v35
	v_fmamk_f32 v35, v88, 0x3fd744fd, v36
	v_fmac_f32_e32 v37, 0x3fd744fd, v89
	s_waitcnt lgkmcnt(0)
	v_fmamk_f32 v36, v66, 0x3fd744fd, v38
	v_lshlrev_b64 v[46:47], 11, v[44:45]
	v_fmamk_f32 v38, v67, 0x3fd744fd, v39
	v_fmamk_f32 v39, v68, 0x3fd744fd, v40
	v_fmac_f32_e32 v41, 0x3fd744fd, v69
	v_cvt_pk_bf16_f32 v34, v0, v34
	v_cvt_pk_bf16_f32 v35, v35, v37
	v_cvt_pk_bf16_f32 v36, v36, v38
	v_cvt_pk_bf16_f32 v37, v39, v41
	v_lshl_add_u64 v[46:47], v[42:43], 0, v[46:47]
	ds_read_b128 v[38:41], v48 offset:16896
	global_store_dwordx4 v[46:47], v[34:37], off
	ds_read_b128 v[34:37], v48 offset:16912
	s_waitcnt vmcnt(6) lgkmcnt(1)
	v_fmamk_f32 v0, v78, 0x3fd744fd, v38
	v_fmamk_f32 v38, v79, 0x3fd744fd, v39
	s_waitcnt vmcnt(5) lgkmcnt(0)
	v_fmamk_f32 v46, v72, 0x3fd744fd, v36
	v_fmac_f32_e32 v37, 0x3fd744fd, v73
	v_cvt_pk_bf16_f32 v37, v46, v37
	v_add_u32_e32 v46, 32, v44
	v_ashrrev_i32_e32 v47, 31, v46
	v_lshlrev_b64 v[46:47], 11, v[46:47]
	v_fmamk_f32 v39, v80, 0x3fd744fd, v40
	v_fmac_f32_e32 v41, 0x3fd744fd, v81
	v_fmamk_f32 v40, v70, 0x3fd744fd, v34
	v_fmamk_f32 v45, v71, 0x3fd744fd, v35
	v_cvt_pk_bf16_f32 v34, v0, v38
	v_cvt_pk_bf16_f32 v35, v39, v41
	v_cvt_pk_bf16_f32 v36, v40, v45
	v_lshl_add_u64 v[46:47], v[42:43], 0, v[46:47]
	ds_read_b128 v[38:41], v48 offset:33792
	global_store_dwordx4 v[46:47], v[34:37], off
	ds_read_b128 v[34:37], v48 offset:33808
	s_waitcnt vmcnt(5) lgkmcnt(1)
	v_fmamk_f32 v0, v90, 0x3fd744fd, v38
	v_fmamk_f32 v38, v91, 0x3fd744fd, v39
	s_waitcnt vmcnt(4) lgkmcnt(0)
	v_fmamk_f32 v46, v76, 0x3fd744fd, v36
	v_fmac_f32_e32 v37, 0x3fd744fd, v77
	v_cvt_pk_bf16_f32 v37, v46, v37
	v_add_u32_e32 v46, 64, v44
	v_ashrrev_i32_e32 v47, 31, v46
	v_fmamk_f32 v39, v92, 0x3fd744fd, v40
	v_fmac_f32_e32 v41, 0x3fd744fd, v93
	v_fmamk_f32 v40, v74, 0x3fd744fd, v34
	v_lshlrev_b64 v[46:47], 11, v[46:47]
	v_fmamk_f32 v45, v75, 0x3fd744fd, v35
	v_cvt_pk_bf16_f32 v34, v0, v38
	v_cvt_pk_bf16_f32 v35, v39, v41
	v_cvt_pk_bf16_f32 v36, v40, v45
	ds_read_b128 v[38:41], v48 offset:50688
	v_lshl_add_u64 v[46:47], v[42:43], 0, v[46:47]
	global_store_dwordx4 v[46:47], v[34:37], off
	ds_read_b128 v[34:37], v48 offset:50704
	s_waitcnt vmcnt(4) lgkmcnt(1)
	v_fmamk_f32 v0, v94, 0x3fd744fd, v38
	v_fmamk_f32 v38, v95, 0x3fd744fd, v39
	v_fmamk_f32 v39, v96, 0x3fd744fd, v40
	s_waitcnt vmcnt(3) lgkmcnt(0)
	v_fmamk_f32 v40, v82, 0x3fd744fd, v34
	v_cvt_pk_bf16_f32 v34, v0, v38
	v_add_u32_e32 v38, 0x60, v44
	v_fmac_f32_e32 v41, 0x3fd744fd, v97
	v_fmamk_f32 v45, v83, 0x3fd744fd, v35
	v_cvt_pk_bf16_f32 v35, v39, v41
	v_ashrrev_i32_e32 v39, 31, v38
	v_lshlrev_b64 v[38:39], 11, v[38:39]
	v_fmac_f32_e32 v37, 0x3fd744fd, v85
	v_lshl_add_u64 v[38:39], v[42:43], 0, v[38:39]
	v_mov_b32_e32 v0, v168
	v_fmamk_f32 v46, v84, 0x3fd744fd, v36
	v_cvt_pk_bf16_f32 v36, v40, v45
	v_cvt_pk_bf16_f32 v37, v46, v37
	global_store_dwordx4 v[38:39], v[34:37], off
	s_nop 1
	v_lshlrev_b32_e32 v34, 3, v0
	v_ashrrev_i32_e32 v0, 4, v0
	v_add_u32_e32 v66, s35, v0
	v_and_b32_e32 v68, 0x78, v34
	v_ashrrev_i32_e32 v67, 31, v66
	s_cbranch_vccnz .LBB0_83
	s_add_u32 s0, s12, s24
	s_addc_u32 s1, s13, s25
	v_lshlrev_b32_e32 v0, 1, v68
	v_lshl_add_u64 v[34:35], s[0:1], 0, v[0:1]
	v_lshlrev_b64 v[36:37], 11, v[66:67]
	v_lshl_add_u64 v[38:39], v[34:35], 0, v[36:37]
	v_add_co_u32_e32 v40, vcc, s88, v38
	s_mov_b32 s0, 0x20000
	s_nop 0
	v_addc_co_u32_e32 v41, vcc, 0, v39, vcc
	v_add_co_u32_e32 v40, vcc, s0, v38
	s_mov_b32 s0, 0x30000
	s_nop 0
	v_addc_co_u32_e32 v41, vcc, 0, v39, vcc
	v_add_co_u32_e32 v38, vcc, s0, v38
	s_nop 0
	s_nop 0
	v_addc_co_u32_e32 v39, vcc, 0, v39, vcc
	s_waitcnt vmcnt(0)
	v_and_b32_e32 v63, 0xffff0000, v186
	v_lshlrev_b32_e32 v62, 16, v186
	v_and_b32_e32 v65, 0xffff0000, v187
	v_lshlrev_b32_e32 v64, 16, v187
	v_and_b32_e32 v39, 0xffff0000, v188
	v_lshlrev_b32_e32 v38, 16, v188
	v_and_b32_e32 v41, 0xffff0000, v189
	v_lshlrev_b32_e32 v40, 16, v189
	s_waitcnt vmcnt(0)
	v_and_b32_e32 v51, 0xffff0000, v190
	v_lshlrev_b32_e32 v50, 16, v190
	v_and_b32_e32 v53, 0xffff0000, v191
	v_lshlrev_b32_e32 v52, 16, v191
	v_and_b32_e32 v35, 0xffff0000, v192
	v_lshlrev_b32_e32 v34, 16, v192
	v_and_b32_e32 v37, 0xffff0000, v193
	v_lshlrev_b32_e32 v36, 16, v193
	s_waitcnt vmcnt(0)
	v_and_b32_e32 v55, 0xffff0000, v194
	v_lshlrev_b32_e32 v54, 16, v194
	v_and_b32_e32 v57, 0xffff0000, v195
	v_lshlrev_b32_e32 v56, 16, v195
	v_and_b32_e32 v43, 0xffff0000, v196
	v_lshlrev_b32_e32 v42, 16, v196
	v_and_b32_e32 v45, 0xffff0000, v197
	v_lshlrev_b32_e32 v44, 16, v197
	s_waitcnt vmcnt(0)
	v_and_b32_e32 v59, 0xffff0000, v198
	v_lshlrev_b32_e32 v58, 16, v198
	v_and_b32_e32 v61, 0xffff0000, v199
	v_lshlrev_b32_e32 v60, 16, v199
	v_and_b32_e32 v47, 0xffff0000, v200
	v_lshlrev_b32_e32 v46, 16, v200
	v_and_b32_e32 v49, 0xffff0000, v201
	v_lshlrev_b32_e32 v48, 16, v201
	s_cbranch_execnz .LBB0_62
	s_branch .LBB0_61
